# P0: SSM table set-up moved to the last 128 waves (which have one weight item fewer)
# baseline (speedup 1.0000x reference)
; __device__ __forceinline__ void ssm_tables(int idx, const float* a_re, const float* a_im, const float* b_re, const float* b_im, const float* log_dt, float* ABAR, bf16_t* BBH, bf16_t* BBL) {
;     const int g = idx >> 6, p = idx & 63;
;     const float dt = expf(log_dt[g]), are = a_re[idx], aim = a_im[idx];
;     const float mag = expf(dt * are), ang = dt * aim, ar = mag * cosf(ang), ai = mag * sinf(ang);
; __global__ void __launch_bounds__(NTHREADS, 2) mega_fwd(Args a) {
;     ...
;         if (gw * 64 + lane < NG * NS) ssm_tables(gw * 64 + lane, a.in[11], a.in[12], a.in[13], a.in[14], a.in[18], (float*)(ws + WS_ABAR), (bf16_t*)(ws + WS_BBH), (bf16_t*)(ws + WS_BBL));
.LBB0_109:
	v_readlane_b32 s92, v249, 24
	s_movk_i32 s0, 0x800
	v_readlane_b32 s93, v249, 25
	s_add_i32 s92, s92, 0x80
	s_cmp_ge_i32 s92, s33
	s_cselect_b32 s1, s33, 0
	s_sub_i32 s92, s92, s1
	v_lshl_or_b32 v0, s92, 6, v196
	v_cmp_gt_i32_e32 vcc, s0, v0
	s_and_saveexec_b64 s[10:11], vcc
	s_cbranch_execz .LBB0_119
	s_ashr_i32 s93, s92, 31
	s_lshl_b64 s[0:1], s[92:93], 2
	s_add_u32 s0, s40, s0
	s_addc_u32 s1, s41, s1
	v_mov_b32_e32 v5, 0
	global_load_dword v4, v5, s[0:1]
	v_ashrrev_i32_e32 v1, 31, v0
	v_readlane_b32 s48, v249, 2
	v_lshlrev_b64 v[6:7], 2, v[0:1]
	v_readlane_b32 s56, v249, 10
	v_readlane_b32 s57, v249, 11
	v_readlane_b32 s54, v249, 8
	v_readlane_b32 s55, v249, 9
	v_lshl_add_u64 v[2:3], s[56:57], 0, v[6:7]
	global_load_dword v3, v[2:3], off
	v_lshl_add_u64 v[6:7], s[54:55], 0, v[6:7]
	global_load_dword v2, v[6:7], off
	s_mov_b32 s0, 0x3fb8aa3b
	s_mov_b32 s1, 0xc2ce8ed0
	s_brev_b32 s3, 18
	v_readlane_b32 s49, v249, 3
	v_readlane_b32 s50, v249, 4
	v_readlane_b32 s51, v249, 5
	v_readlane_b32 s52, v249, 6
	v_readlane_b32 s53, v249, 7
	v_readlane_b32 s58, v249, 12
	v_readlane_b32 s59, v249, 13
	v_readlane_b32 s60, v249, 14
	v_readlane_b32 s61, v249, 15
	v_readlane_b32 s62, v249, 16
	v_readlane_b32 s63, v249, 17
	s_waitcnt vmcnt(2)
	v_mul_f32_e32 v6, 0x3fb8aa3b, v4
	v_fma_f32 v7, v4, s0, -v6
	v_rndne_f32_e32 v8, v6
	v_fmamk_f32 v7, v4, 0x32a5705f, v7
	v_sub_f32_e32 v6, v6, v8
	v_add_f32_e32 v6, v6, v7
	v_cvt_i32_f32_e32 v8, v8
	v_exp_f32_e32 v6, v6
	s_mov_b32 s0, 0x42b17218
	v_cmp_ngt_f32_e32 vcc, s1, v4
	v_mov_b32_e32 v7, 0x7f800000
	v_ldexp_f32 v6, v6, v8
	v_cndmask_b32_e32 v6, 0, v6, vcc
	v_cmp_nlt_f32_e32 vcc, s0, v4
	s_nop 1
	v_cndmask_b32_e32 v6, v7, v6, vcc
	s_waitcnt vmcnt(1)
	v_mul_f32_e32 v8, v6, v3
	v_and_b32_e32 v9, 0x7fffffff, v8
	v_cmp_nlt_f32_e64 s[12:13], |v8|, s3
	v_lshrrev_b32_e32 v11, 23, v9
	s_and_saveexec_b64 s[0:1], s[12:13]
	s_xor_b64 s[14:15], exec, s[0:1]
	s_cbranch_execz .LBB0_112
	v_add_u32_e32 v4, 0xffffff88, v11
	v_not_b32_e32 v7, 63
	v_cmp_lt_u32_e32 vcc, 63, v4
	s_mov_b32 s3, 0xfe5163ab
	s_nop 0
	v_cndmask_b32_e32 v7, 0, v7, vcc
	v_add_u32_e32 v4, v7, v4
	v_not_b32_e32 v7, 31
	v_cmp_lt_u32_e64 s[0:1], 31, v4
	s_nop 1
	v_cndmask_b32_e64 v10, 0, v7, s[0:1]
	v_add_u32_e32 v4, v10, v4
	v_cmp_lt_u32_e64 s[4:5], 31, v4
	s_nop 1
	v_cndmask_b32_e64 v7, 0, v7, s[4:5]
	v_add_u32_e32 v7, v7, v4
	v_and_b32_e32 v4, 0x7fffff, v9
	v_or_b32_e32 v10, 0x800000, v4
	v_mad_u64_u32 v[12:13], s[6:7], v10, s3, 0
	v_mov_b32_e32 v4, v13
	s_mov_b32 s3, 0x3c439041
	v_mad_u64_u32 v[14:15], s[6:7], v10, s3, v[4:5]
	v_mov_b32_e32 v4, v15
	s_mov_b32 s3, 0xdb629599
	v_mad_u64_u32 v[16:17], s[6:7], v10, s3, v[4:5]
	v_mov_b32_e32 v4, v17
	s_mov_b32 s3, 0xf534ddc0
	v_mad_u64_u32 v[18:19], s[6:7], v10, s3, v[4:5]
	v_mov_b32_e32 v4, v19
	s_mov_b32 s3, 0xfc2757d1
	v_mad_u64_u32 v[20:21], s[6:7], v10, s3, v[4:5]
	v_mov_b32_e32 v4, v21
	s_mov_b32 s3, 0x4e441529
	v_mad_u64_u32 v[22:23], s[6:7], v10, s3, v[4:5]
	v_mov_b32_e32 v4, v23
	s_mov_b32 s3, 0xa2f9836e
	v_mad_u64_u32 v[4:5], s[6:7], v10, s3, v[4:5]
	v_cndmask_b32_e32 v13, v22, v18, vcc
	v_cndmask_b32_e32 v4, v4, v20, vcc
	v_cndmask_b32_e32 v5, v5, v22, vcc
	v_cndmask_b32_e64 v10, v4, v13, s[0:1]
	v_cndmask_b32_e64 v4, v5, v4, s[0:1]
	v_cndmask_b32_e32 v5, v20, v16, vcc
	v_cndmask_b32_e64 v13, v13, v5, s[0:1]
	v_cndmask_b32_e64 v4, v4, v10, s[4:5]
	v_cndmask_b32_e64 v10, v10, v13, s[4:5]
	v_sub_u32_e32 v15, 32, v7
	v_alignbit_b32 v17, v4, v10, v15
	v_cmp_eq_u32_e64 s[6:7], 0, v7
	v_cndmask_b32_e32 v12, v16, v12, vcc
	s_nop 0
	v_cndmask_b32_e64 v7, v17, v4, s[6:7]
	v_cndmask_b32_e32 v4, v18, v14, vcc
	v_cndmask_b32_e64 v5, v5, v4, s[0:1]
	v_cndmask_b32_e64 v13, v13, v5, s[4:5]
	v_alignbit_b32 v14, v10, v13, v15
	v_cndmask_b32_e64 v10, v14, v10, s[6:7]
	v_bfe_u32 v18, v7, 29, 1
	v_cndmask_b32_e64 v4, v4, v12, s[0:1]
	v_alignbit_b32 v14, v7, v10, 30
	v_sub_u32_e32 v19, 0, v18
	v_cndmask_b32_e64 v4, v5, v4, s[4:5]
	v_xor_b32_e32 v14, v14, v19
	v_alignbit_b32 v5, v13, v4, v15
	v_cndmask_b32_e64 v5, v5, v13, s[6:7]
	v_ffbh_u32_e32 v12, v14
	v_alignbit_b32 v10, v10, v5, 30
	v_min_u32_e32 v12, 32, v12
	v_alignbit_b32 v4, v5, v4, 30
	v_xor_b32_e32 v10, v10, v19
	v_sub_u32_e32 v13, 31, v12
	v_xor_b32_e32 v4, v4, v19
	v_alignbit_b32 v14, v14, v10, v13
	v_alignbit_b32 v4, v10, v4, v13
	v_alignbit_b32 v5, v14, v4, 9
	v_ffbh_u32_e32 v10, v5
	v_min_u32_e32 v10, 32, v10
	v_lshrrev_b32_e32 v17, 29, v7
	v_not_b32_e32 v13, v10
	v_alignbit_b32 v4, v5, v4, v13
	v_lshlrev_b32_e32 v5, 31, v17
	v_or_b32_e32 v13, 0x33000000, v5
	v_add_lshl_u32 v10, v10, v12, 23
	v_lshrrev_b32_e32 v4, 9, v4
	v_sub_u32_e32 v10, v13, v10
	v_or_b32_e32 v5, 0.5, v5
	v_lshlrev_b32_e32 v12, 23, v12
	v_or_b32_e32 v4, v10, v4
	v_lshrrev_b32_e32 v10, 9, v14
	v_sub_u32_e32 v5, v5, v12
	v_or_b32_e32 v5, v10, v5
	s_mov_b32 s0, 0x3fc90fda
	v_mul_f32_e32 v10, 0x3fc90fda, v5
	v_fma_f32 v12, v5, s0, -v10
	v_fmamk_f32 v5, v5, 0x33a22168, v12
	v_fmac_f32_e32 v5, 0x3fc90fda, v4
	v_add_f32_e32 v4, v10, v5
	v_lshrrev_b32_e32 v5, 30, v7
	v_add_u32_e32 v10, v18, v5
	s_andn2_saveexec_b64 s[0:1], s[14:15]
	s_cbranch_execz .LBB0_114
	s_branch .LBB0_113

; __global__ void __launch_bounds__(NTHREADS, 2) mega_fwd(Args a) {
;     ...
;         for (int i = gw * 64 + lane; i < NB * NH * 8 * HD; i += NGW * 64) KM[i] = 0.f;
.LBB0_121:
	s_or_b64 exec, exec, s[0:1]
	v_readlane_b32 s92, v249, 24
	s_nop 1
	v_lshl_or_b32 v0, s92, 6, v196
	s_mov_b32 s0, 0x20000
	v_cmp_gt_i32_e32 vcc, s0, v0
	s_and_saveexec_b64 s[4:5], vcc
	s_cbranch_execz .LBB0_129
	s_lshl_b32 s6, s22, 9
	v_cvt_f32_u32_e32 v1, s6
	s_add_i32 s1, s2, s22
	s_and_b32 s3, s97, 0xffffffc0
	s_lshl_b32 s1, s1, 9
	v_rcp_iflag_f32_e32 v1, v1
	s_add_i32 s1, s1, s3
	v_or_b32_e32 v2, s1, v196
	v_cmp_gt_i32_e32 vcc, s0, v2
	v_mul_f32_e32 v1, 0x4f7ffffe, v1
	v_cvt_u32_f32_e32 v1, v1
	v_max_i32_e32 v3, 0x20000, v2
	v_addc_co_u32_e64 v2, s[0:1], 0, v2, vcc
	s_sub_i32 s0, 0, s6
	v_sub_u32_e32 v2, v3, v2
	v_mul_lo_u32 v3, s0, v1
	v_mul_hi_u32 v3, v1, v3
	v_add_u32_e32 v1, v1, v3
	v_mul_hi_u32 v1, v2, v1
	v_mul_lo_u32 v3, v1, s6
	v_sub_u32_e32 v2, v2, v3
	v_add_u32_e32 v3, 1, v1
	v_cmp_le_u32_e64 s[0:1], s6, v2
	s_mov_b64 s[10:11], -1
	s_nop 0
	v_cndmask_b32_e64 v1, v1, v3, s[0:1]
	v_subrev_u32_e32 v3, s6, v2
	v_cndmask_b32_e64 v2, v2, v3, s[0:1]
	v_add_u32_e32 v3, 1, v1
	v_cmp_le_u32_e64 s[0:1], s6, v2
	s_nop 1
	v_cndmask_b32_e64 v1, v1, v3, s[0:1]
	v_addc_co_u32_e32 v4, vcc, 1, v1, vcc
	v_cmp_lt_u32_e32 vcc, 1, v4
	s_and_saveexec_b64 s[0:1], vcc
	s_cbranch_execz .LBB0_126
	v_and_b32_e32 v5, -2, v4
	v_add_u32_e32 v1, s6, v0
	s_lshl_b32 s3, s22, 10
	s_mov_b32 s7, s3
	s_mov_b64 s[10:11], 0
	v_mov_b32_e32 v6, 0
	v_mov_b32_e32 v7, v5
	v_mov_b64_e32 v[2:3], v[0:1]
